# grid barrier: XCD leader publishes the per-XCD generation before issuing its own L1 invalidate (13 sites)
# speedup vs baseline: 1.0015x; 1.0015x over previous
; __device__ __forceinline__ unsigned xb_ld(unsigned* p)              { return __hip_atomic_load(p, __ATOMIC_RELAXED, __HIP_MEMORY_SCOPE_AGENT); }
; __device__ __forceinline__ unsigned xb_add(unsigned* p, unsigned v) { return __hip_atomic_fetch_add(p, v, __ATOMIC_RELAXED, __HIP_MEMORY_SCOPE_AGENT); }
; #define XB_SPIN(cond, bar) do { unsigned _sp = 0; while (cond) { __builtin_amdgcn_s_sleep(1); \
;     if ((++_sp & 255u) == 0u) { if (xb_ld(&(bar)[XB_TMO])) break; if (_sp > XB_SPIN_CAP) { atomicAdd(&(bar)[XB_TMO], 1u); break; } } } } while (0)
; __device__ __forceinline__ void xcd_barrier(const XcdBarrier& b) {
;     ...
;         const unsigned old = xb_add(&bar[XB_XSUB(b.x)], 1u);
;         const unsigned gen = old / nloc;
;         if (old + 1u == (gen + 1u) * nloc) {
;             __builtin_amdgcn_fence(__ATOMIC_RELEASE, "agent");
;             asm volatile("s_waitcnt vmcnt(0)" ::: "memory");
;             const unsigned og = xb_add(&bar[XB_TOP], 1u);
;             const unsigned tg = og / nx;
;             if (og + 1u == (tg + 1u) * nx) xb_add(&bar[XB_TOPGEN], 1u);
;             else XB_SPIN(xb_ld(&bar[XB_TOPGEN]) == tg, bar);
;             __builtin_amdgcn_fence(__ATOMIC_ACQUIRE, "agent");
;             xb_add(&bar[XB_XGEN(b.x)], 1u);
;             asm volatile("s_waitcnt vmcnt(0)" ::: "memory");
.LBB0_8:
	s_or_b64 exec, exec, s[2:3]
	v_mov_b32_e32 v1, s25
	v_add_co_u32_e32 v4, vcc, 0x2000, v1
	v_mov_b32_e32 v1, s24
	s_nop 0
	v_addc_co_u32_e32 v5, vcc, 0, v1, vcc
	s_waitcnt vmcnt(0) lgkmcnt(0)
	flat_atomic_add v[4:5], v210 offset:1024
	buffer_inv sc1
	s_waitcnt vmcnt(0)

; __device__ __forceinline__ unsigned xb_ld(unsigned* p)              { return __hip_atomic_load(p, __ATOMIC_RELAXED, __HIP_MEMORY_SCOPE_AGENT); }
; __device__ __forceinline__ unsigned xb_add(unsigned* p, unsigned v) { return __hip_atomic_fetch_add(p, v, __ATOMIC_RELAXED, __HIP_MEMORY_SCOPE_AGENT); }
; #define XB_SPIN(cond, bar) do { unsigned _sp = 0; while (cond) { __builtin_amdgcn_s_sleep(1); \
;     if ((++_sp & 255u) == 0u) { if (xb_ld(&(bar)[XB_TMO])) break; if (_sp > XB_SPIN_CAP) { atomicAdd(&(bar)[XB_TMO], 1u); break; } } } } while (0)
; __device__ __forceinline__ void xcd_barrier(const XcdBarrier& b) {
;     ...
;             const unsigned og = xb_add(&bar[XB_TOP], 1u);
;             const unsigned tg = og / nx;
;             if (og + 1u == (tg + 1u) * nx) xb_add(&bar[XB_TOPGEN], 1u);
;             else XB_SPIN(xb_ld(&bar[XB_TOPGEN]) == tg, bar);
;             __builtin_amdgcn_fence(__ATOMIC_ACQUIRE, "agent");
;             xb_add(&bar[XB_XGEN(b.x)], 1u);
;             asm volatile("s_waitcnt vmcnt(0)" ::: "memory");
.LBB0_304:
	s_or_b64 exec, exec, s[6:7]
	v_mov_b32_e32 v1, s30
	v_add_co_u32_e32 v4, vcc, 0x2000, v1
	v_mov_b32_e32 v1, s13
	s_nop 0
	v_addc_co_u32_e32 v5, vcc, 0, v1, vcc
	s_waitcnt vmcnt(0) lgkmcnt(0)
	flat_atomic_add v[4:5], v210 offset:1024
	buffer_inv sc1
	s_waitcnt vmcnt(0)

; __device__ __forceinline__ unsigned xb_ld(unsigned* p)              { return __hip_atomic_load(p, __ATOMIC_RELAXED, __HIP_MEMORY_SCOPE_AGENT); }
; __device__ __forceinline__ unsigned xb_add(unsigned* p, unsigned v) { return __hip_atomic_fetch_add(p, v, __ATOMIC_RELAXED, __HIP_MEMORY_SCOPE_AGENT); }
; #define XB_SPIN(cond, bar) do { unsigned _sp = 0; while (cond) { __builtin_amdgcn_s_sleep(1); \
;     if ((++_sp & 255u) == 0u) { if (xb_ld(&(bar)[XB_TMO])) break; if (_sp > XB_SPIN_CAP) { atomicAdd(&(bar)[XB_TMO], 1u); break; } } } } while (0)
; __device__ __forceinline__ void xcd_barrier(const XcdBarrier& b) {
;     ...
;             const unsigned og = xb_add(&bar[XB_TOP], 1u);
;             const unsigned tg = og / nx;
;             if (og + 1u == (tg + 1u) * nx) xb_add(&bar[XB_TOPGEN], 1u);
;             else XB_SPIN(xb_ld(&bar[XB_TOPGEN]) == tg, bar);
;             __builtin_amdgcn_fence(__ATOMIC_ACQUIRE, "agent");
;             xb_add(&bar[XB_XGEN(b.x)], 1u);
;             asm volatile("s_waitcnt vmcnt(0)" ::: "memory");
.LBB0_1504:
	s_or_b64 exec, exec, s[4:5]
	v_mov_b32_e32 v1, s27
	v_add_co_u32_e32 v4, vcc, 0x2000, v1
	v_mov_b32_e32 v1, s26
	s_nop 0
	v_addc_co_u32_e32 v5, vcc, 0, v1, vcc
	s_waitcnt vmcnt(0) lgkmcnt(0)
	flat_atomic_add v[4:5], v210 offset:1024
	buffer_inv sc1
	s_waitcnt vmcnt(0)

; __device__ __forceinline__ unsigned xb_ld(unsigned* p)              { return __hip_atomic_load(p, __ATOMIC_RELAXED, __HIP_MEMORY_SCOPE_AGENT); }
; __device__ __forceinline__ unsigned xb_add(unsigned* p, unsigned v) { return __hip_atomic_fetch_add(p, v, __ATOMIC_RELAXED, __HIP_MEMORY_SCOPE_AGENT); }
; #define XB_SPIN(cond, bar) do { unsigned _sp = 0; while (cond) { __builtin_amdgcn_s_sleep(1); \
;     if ((++_sp & 255u) == 0u) { if (xb_ld(&(bar)[XB_TMO])) break; if (_sp > XB_SPIN_CAP) { atomicAdd(&(bar)[XB_TMO], 1u); break; } } } } while (0)
; __device__ __forceinline__ void xcd_barrier(const XcdBarrier& b) {
;     ...
;             const unsigned og = xb_add(&bar[XB_TOP], 1u);
;             const unsigned tg = og / nx;
;             if (og + 1u == (tg + 1u) * nx) xb_add(&bar[XB_TOPGEN], 1u);
;             else XB_SPIN(xb_ld(&bar[XB_TOPGEN]) == tg, bar);
;             __builtin_amdgcn_fence(__ATOMIC_ACQUIRE, "agent");
;             xb_add(&bar[XB_XGEN(b.x)], 1u);
;             asm volatile("s_waitcnt vmcnt(0)" ::: "memory");
.LBB0_1585:
	s_or_b64 exec, exec, s[6:7]
	v_mov_b32_e32 v1, s29
	v_add_co_u32_e32 v4, vcc, 0x2000, v1
	v_mov_b32_e32 v1, s28
	s_nop 0
	v_addc_co_u32_e32 v5, vcc, 0, v1, vcc
	s_waitcnt vmcnt(0) lgkmcnt(0)
	flat_atomic_add v[4:5], v210 offset:1024
	buffer_inv sc1
	s_waitcnt vmcnt(0)
